# mixer_local next-unit prefetch also covers gdn/conf halo rows and gdn beta/decay logits
# speedup vs baseline: 1.0033x; 1.0033x over previous
; __device__ __forceinline__ void gdn_unit(const Ctx& X, LAS unsigned char* hl, int b, int c, int h, int tid_h, int w4, int lane, int layer) {
;     ...
;         for (int n = 0; n < 7; ++n) { const int item = tid_h + 256 * n; const int seg = item & 7; int rowid = item >> 3; rowid = rowid < 201 ? rowid : 200;
;             const int tn = rowid / 67, rr = rowid - tn * 67; const int tt = c * 64 - 3 + rr; const int ttc = tt < 0 ? 0 : tt;
;             const u32x4 v = *(const u32x4*)(proj + ((size_t)b * T + ttc) * LDP + C_GQ + tn * 256 + h * 64 + seg * 8);
;             rawv[n] = tt < 0 ? (u32x4){0u, 0u, 0u, 0u} : v; }
;         float g = 0.f, bt = 0.f;
;         if (tid_h < 64) {
;             const bf16_t* pr = proj + ((size_t)b * T + c * 64 + tid_h) * LDP;
;             const float* gba = WSP(const float, WS_GBA) + ((size_t)b * T + c * 64 + tid_h) * 8; const float gb = gba[h], ga = gba[4 + h];
; __device__ __forceinline__ void mixer_local_phase(const Ctx& X, LAS unsigned char* lds, int layer, int tid, int wave, int lane) {
;     ...
;     const int nit_ = (3584 + (int)gridDim.x - 1) / (int)gridDim.x;
;     for (int it_ = 0; it_ < nit_; ++it_) {
;         const int u = (int)blockIdx.x + (int)gridDim.x * ((it_ + (int)(blockIdx.x >> 3)) % nit_);
;         if (u >= 3584) continue;
;         asm volatile("" : "+v"(tid_h), "+v"(lane), "+v"(tid));
;         if (u < 3072) { const int mixer = u >> 10, idx = u & 1023, hp = idx & 1, cb = idx >> 1, b = cb >> 7, c = cb & 127, h = hp * 2 + hs;
.LBB0_261:
	s_or_b64 exec, exec, s[0:1]
	s_waitcnt vmcnt(0)
	v_ashrrev_i32_e32 v6, 8, v180
	v_lshlrev_b32_e32 v7, 14, v6
	v_lshlrev_b32_sdwa v8, v228, v180 dst_sel:DWORD dst_unused:UNUSED_PAD src0_sel:DWORD src1_sel:BYTE_0
	s_waitcnt lgkmcnt(0)
	s_barrier
	s_add_i32 s98, s20, 1
	s_cmp_ge_u32 s98, s70
	s_cbranch_scc1 .LpfC_done
	s_add_i32 s98, s98, s37
	s_mul_hi_u32 s99, s98, s87
	s_mul_i32 s99, s99, s70
	s_sub_i32 s98, s98, s99
	s_sub_i32 s99, s98, s70
	s_cmp_ge_u32 s98, s70
	s_cselect_b32 s98, s99, s98
	s_sub_i32 s99, s98, s70
	s_cmp_ge_u32 s98, s70
	s_cselect_b32 s98, s99, s98
	s_mul_i32 s98, s98, s18
	s_add_i32 s98, s98, s2
	v_lshrrev_b32_e32 v237, 3, v224
	v_and_b32_e32 v238, 7, v224
	s_cmpk_ge_u32 s98, 0xc00
	s_cbranch_scc1 .LpfC_conf
	s_lshr_b32 s99, s98, 10
	s_and_b32 s98, s98, 0x3ff
	s_and_b32 s100, s98, 1
	s_lshr_b32 s98, s98, 1
	s_cmp_eq_u32 s99, 2
	s_mul_i32 s99, s99, 0xc00
	s_cselect_b32 s101, 0x400, 0
	s_sub_u32 s99, s99, s101
	s_lshl_b32 s100, s100, 8
	s_add_u32 s99, s99, s100
	v_min_u32_e32 v238, 5, v238
	v_lshrrev_b32_e32 v239, 1, v238
	v_and_b32_e32 v238, 1, v238
	v_lshlrev_b32_e32 v239, 9, v239
	v_lshl_or_b32 v238, v238, 7, v239
	s_mov_b32 s101, 0
	s_branch .LpfC_go
.LpfC_conf:
	s_sub_u32 s98, s98, 0xc00
	s_movk_i32 s99, 0x800
	s_mov_b32 s101, 1
	v_lshlrev_b32_e32 v238, 7, v238
.LpfC_go:
	s_lshr_b32 s100, s98, 7
	s_lshl_b32 s100, s100, 13
	s_and_b32 s98, s98, 0x7f
	s_lshl_b32 s98, s98, 6
	s_add_u32 s98, s98, s100
	s_mov_b32 s32, s98
	s_mul_i32 s98, s98, 0x1c00
	s_add_u32 s98, s98, s99
	s_add_u32 s82, s76, s98
	s_addc_u32 s83, s77, 0
	v_mad_u32_u24 v237, v237, s71, v238
	global_load_dword v236, v237, s[82:83]
	v_readfirstlane_b32 s100, v224
	s_cmp_eq_u32 s101, 1
	s_cbranch_scc1 .LpfC_chalo
	s_cmpk_ge_u32 s100, 64
	s_cbranch_scc1 .LpfC_gba
	s_sub_u32 s82, s82, 0x5400
	s_subb_u32 s83, s83, 0
	v_lshrrev_b32_e32 v239, 3, v224
	v_min_u32_e32 v239, 2, v239
	v_mad_u32_u24 v239, v239, s71, v238
	global_load_dword v236, v239, s[82:83]
	s_branch .LpfC_done
.LpfC_gba:
	s_cmpk_ge_u32 s100, 128
	s_cbranch_scc1 .LpfC_done
	s_lshl_b32 s32, s32, 5
	s_add_u32 s32, s32, 0x1f740000
	s_add_u32 s82, s30, s32
	s_addc_u32 s83, s31, 0
	v_and_b32_e32 v239, 63, v224
	v_min_u32_e32 v239, 15, v239
	v_lshlrev_b32_e32 v239, 7, v239
	global_load_dword v236, v239, s[82:83]
	s_branch .LpfC_done
.LpfC_chalo:
	s_cmpk_ge_u32 s100, 256
	s_cbranch_scc1 .LpfC_done
	s_sub_u32 s82, s82, 0x38000
	s_subb_u32 s83, s83, 0
	global_load_dword v236, v237, s[82:83]

; __device__ __forceinline__ float fexp(float x) { return __expf(x); }
; __device__ __forceinline__ float frcp(float x) { return __builtin_amdgcn_rcpf(x); }
; __device__ __forceinline__ float sigmoid_f(float x) { return frcp(1.0f + fexp(-x)); }
; #define LBAR() do { asm volatile("s_waitcnt lgkmcnt(0)" ::: "memory"); __builtin_amdgcn_s_barrier(); asm volatile("" ::: "memory"); } while (0)
; __device__ __forceinline__ void hgrn_unit(const Ctx& X, LAS unsigned char* hl, int b, int c, int h, int tid_h, int w4, int lane, int layer) {
;     ...
;         for (int e = 0; e < 16; ++e) {
;             const int ch = h * 64 + ds + e;
;             const float lb = layer == 0 ? 0.f : sigmoid_f(X.in[12][256 + ch] - X.in[12][ch]);
;             const float f = ff[e];
;             const float ls = fminf(f, 0.f) - __logf(1.0f + fexp(-fabsf(f)));
;             const float lf = layer == 0 ? ls : __logf(lb + (1.f - lb) * fexp(ls));
;             kk[e] = (1.f - lb) * frcp(1.f + fexp(f));
;             Gt[i * 64 + ds + e] = lf;
;         }
;     }
;     LBAR();
; __device__ __forceinline__ void mixer_local_phase(const Ctx& X, LAS unsigned char* lds, int layer, int tid, int wave, int lane) {
;     ...
;     for (int it_ = 0; it_ < nit_; ++it_) {
;         const int u = (int)blockIdx.x + (int)gridDim.x * ((it_ + (int)(blockIdx.x >> 3)) % nit_);
;         if (u >= 3584) continue;
;         asm volatile("" : "+v"(tid_h), "+v"(lane), "+v"(tid));
;         if (u < 3072) { const int mixer = u >> 10, idx = u & 1023, hp = idx & 1, cb = idx >> 1, b = cb >> 7, c = cb & 127, h = hp * 2 + hs;
.LBB0_299:
	v_and_b32_e32 v30, 0xffff0000, v25
	v_mul_f32_e64 v25, |v30|, s66
	v_exp_f32_e32 v25, v25
	v_ashrrev_i32_e32 v75, 6, v132
	v_lshlrev_b32_e32 v84, 2, v132
	v_and_b32_e32 v85, 0xfc, v84
	v_add_f32_e32 v25, 1.0, v25
	v_cmp_gt_f32_e32 vcc, s3, v25
	v_mov_b32_e32 v77, 0
	s_nop 0
	v_cndmask_b32_e64 v31, 0, 32, vcc
	v_ldexp_f32 v25, v25, v31
	v_log_f32_e32 v25, v25
	v_cndmask_b32_e32 v60, 0, v231, vcc
	v_max_f32_e32 v31, v30, v30
	v_min_f32_e32 v31, 0, v31
	v_mul_f32_e32 v61, 0x3f317217, v25
	v_fma_f32 v61, v25, s0, -v61
	v_fmac_f32_e32 v61, 0x3377d1cf, v25
	v_fmac_f32_e32 v61, 0x3f317217, v25
	v_cmp_lt_f32_e64 vcc, |v25|, s1
	s_nop 1
	v_cndmask_b32_e32 v25, v25, v61, vcc
	v_sub_f32_e32 v25, v25, v60
	v_sub_f32_e32 v25, v31, v25
	v_mul_f32_e32 v31, 0x3fb8aa3b, v25
	v_exp_f32_e32 v60, v31
	v_sub_f32_e32 v31, 1.0, v24
	v_fmac_f32_e32 v24, v60, v31
	v_cmp_gt_f32_e32 vcc, s3, v24
	s_nop 1
	v_cndmask_b32_e64 v60, 0, 32, vcc
	v_ldexp_f32 v24, v24, v60
	v_log_f32_e32 v24, v24
	v_cndmask_b32_e32 v60, 0, v231, vcc
	v_mul_f32_e32 v61, 0x3f317217, v24
	v_fma_f32 v61, v24, s0, -v61
	v_fmac_f32_e32 v61, 0x3377d1cf, v24
	v_fmac_f32_e32 v61, 0x3f317217, v24
	v_cmp_lt_f32_e64 vcc, |v24|, s1
	s_nop 1
	v_cndmask_b32_e32 v24, v24, v61, vcc
	v_sub_f32_e32 v24, v24, v60
	v_cndmask_b32_e64 v24, v24, v25, s[26:27]
	ds_write_b32 v35, v24 offset:60
	v_lshlrev_b32_e32 v24, 12, v75
	s_waitcnt lgkmcnt(0)
	s_barrier
	s_add_i32 s98, s20, 1
	s_cmp_ge_u32 s98, s70
	s_cbranch_scc1 .LpfH_done
	s_add_i32 s98, s98, s37
	s_mul_hi_u32 s99, s98, s87
	s_mul_i32 s99, s99, s70
	s_sub_i32 s98, s98, s99
	s_sub_i32 s99, s98, s70
	s_cmp_ge_u32 s98, s70
	s_cselect_b32 s98, s99, s98
	s_sub_i32 s99, s98, s70
	s_cmp_ge_u32 s98, s70
	s_cselect_b32 s98, s99, s98
	s_mul_i32 s98, s98, s18
	s_add_i32 s98, s98, s2
	v_lshrrev_b32_e32 v237, 3, v224
	v_and_b32_e32 v238, 7, v224
	s_cmpk_ge_u32 s98, 0xc00
	s_cbranch_scc1 .LpfH_conf
	s_lshr_b32 s99, s98, 10
	s_and_b32 s98, s98, 0x3ff
	s_and_b32 s100, s98, 1
	s_lshr_b32 s98, s98, 1
	s_cmp_eq_u32 s99, 2
	s_mul_i32 s99, s99, 0xc00
	s_cselect_b32 s101, 0x400, 0
	s_sub_u32 s99, s99, s101
	s_lshl_b32 s100, s100, 8
	s_add_u32 s99, s99, s100
	v_min_u32_e32 v238, 5, v238
	v_lshrrev_b32_e32 v239, 1, v238
	v_and_b32_e32 v238, 1, v238
	v_lshlrev_b32_e32 v239, 9, v239
	v_lshl_or_b32 v238, v238, 7, v239
	s_mov_b32 s101, 0
	s_branch .LpfH_go

; #define LAS __attribute__((address_space(3)))
; __device__ __forceinline__ float fexp(float x) { return __expf(x); }
; __device__ __forceinline__ float sigmoid_f(float x) { return frcp(1.0f + fexp(-x)); }
; __device__ __forceinline__ float softplus_f(float x) { return fmaxf(x, 0.f) + log1pf(expf(-fabsf(x))); }
; #define LBAR() do { asm volatile("s_waitcnt lgkmcnt(0)" ::: "memory"); __builtin_amdgcn_s_barrier(); asm volatile("" ::: "memory"); } while (0)
; __device__ __forceinline__ void gdn_unit(const Ctx& X, LAS unsigned char* hl, int b, int c, int h, int tid_h, int w4, int lane, int layer) {
;     ...
;         if (tid_h < 64) {
;             const bf16_t* pr = proj + ((size_t)b * T + c * 64 + tid_h) * LDP;
;             const float* gba = WSP(const float, WS_GBA) + ((size_t)b * T + c * 64 + tid_h) * 8; const float gb = gba[h], ga = gba[4 + h];
;             g = -fexp(X.in[9][layer * 4 + h]) * softplus_f(ga + X.in[10][layer * 4 + h]);
; #pragma unroll
;             for (int o = 1; o < 64; o <<= 1) { const float t = __shfl_up(g, o); if (lane >= o) g += t; }
;             bt = sigmoid_f(gb);
;             Gs[tid_h] = g; Bs[tid_h] = bt;
;         }
; #pragma unroll
;         for (int n = 0; n < 7; ++n) { const int item = tid_h + 256 * n; if (item < 1608) *(LAS u32x4*)(RAW + (item >> 3) * 64 + (item & 7) * 8) = rawv[n]; }
;     }
;     LBAR();
; __device__ __forceinline__ void mixer_local_phase(const Ctx& X, LAS unsigned char* lds, int layer, int tid, int wave, int lane) {
;     ...
;     for (int it_ = 0; it_ < nit_; ++it_) {
;         const int u = (int)blockIdx.x + (int)gridDim.x * ((it_ + (int)(blockIdx.x >> 3)) % nit_);
;         if (u >= 3584) continue;
;         asm volatile("" : "+v"(tid_h), "+v"(lane), "+v"(tid));
;         if (u < 3072) { const int mixer = u >> 10, idx = u & 1023, hp = idx & 1, cb = idx >> 1, b = cb >> 7, c = cb & 127, h = hp * 2 + hs;
.LBB0_349:
	s_or_b64 exec, exec, s[0:1]
	s_waitcnt vmcnt(0)
	v_and_b32_e32 v103, 64, v230
	v_xor_b32_e32 v102, 1, v230
	v_add_u32_e32 v103, 64, v103
	v_cmp_lt_i32_e32 vcc, v102, v103
	s_waitcnt lgkmcnt(0)
	s_barrier
	s_add_i32 s98, s20, 1
	s_cmp_ge_u32 s98, s70
	s_cbranch_scc1 .LpfG_done
	s_add_i32 s98, s98, s37
	s_mul_hi_u32 s99, s98, s87
	s_mul_i32 s99, s99, s70
	s_sub_i32 s98, s98, s99
	s_sub_i32 s99, s98, s70
	s_cmp_ge_u32 s98, s70
	s_cselect_b32 s98, s99, s98
	s_sub_i32 s99, s98, s70
	s_cmp_ge_u32 s98, s70
	s_cselect_b32 s98, s99, s98
	s_mul_i32 s98, s98, s18
	s_add_i32 s98, s98, s2
	v_lshrrev_b32_e32 v237, 3, v224
	v_and_b32_e32 v238, 7, v224
	s_cmpk_ge_u32 s98, 0xc00
	s_cbranch_scc1 .LpfG_conf
	s_lshr_b32 s99, s98, 10
	s_and_b32 s98, s98, 0x3ff
	s_and_b32 s100, s98, 1
	s_lshr_b32 s98, s98, 1
	s_cmp_eq_u32 s99, 2
	s_mul_i32 s99, s99, 0xc00
	s_cselect_b32 s101, 0x400, 0
	s_sub_u32 s99, s99, s101
	s_lshl_b32 s100, s100, 8
	s_add_u32 s99, s99, s100
	v_min_u32_e32 v238, 5, v238
	v_lshrrev_b32_e32 v239, 1, v238
	v_and_b32_e32 v238, 1, v238
	v_lshlrev_b32_e32 v239, 9, v239
	v_lshl_or_b32 v238, v238, 7, v239
	s_mov_b32 s101, 0
	s_branch .LpfG_go

; __device__ __forceinline__ float fexp(float x) { return __expf(x); }
; __device__ __forceinline__ int unit_id(int mixer, int b, int h, int c) { return ((mixer * 4 + b) * 4 + h) * NCH + c; }
; __device__ __forceinline__ void ret_unit(const Ctx& X, LAS unsigned char* hl, int b, int c, int h, int tid_h, int w4, int lane) {
;     ...
;     const int uid = unit_id(0, b, h, c);
;     const int r = lane & 15, q = lane >> 4;
;     const float lg = log1pf(-exp2f(-5.0f - (float)h));
;     {
;         const int i = tid_h >> 2, sg = tid_h & 3, d0 = sg * 8;
;         const bf16_t* pr = proj + ((size_t)b * T + c * 64 + i) * LDP;
;         const u32x4 q1 = *(const u32x4*)(pr + C_RQ + h * 64 + d0), q2 = *(const u32x4*)(pr + C_RQ + h * 64 + d0 + 32);
;         const u32x4 k1 = *(const u32x4*)(pr + C_RK + h * 64 + d0), k2 = *(const u32x4*)(pr + C_RK + h * 64 + d0 + 32);
;         const u32x4 v1 = *(const u32x4*)(pr + C_RV + h * 64 + sg * 16), v2 = *(const u32x4*)(pr + C_RV + h * 64 + sg * 16 + 8);
;         float qa[8], qb[8], ka[8], kb[8], va[8], vb[8];
;         unpack8(q1, qa); unpack8(q2, qb); unpack8(k1, ka); unpack8(k2, kb); unpack8(v1, va); unpack8(v2, vb);
;         const float pos = (float)(c * 64 + i);
;         const float qd = fexp(lg * (float)(i + 1)), kd = fexp(lg * (float)(63 - i));
.LBB0_621:
	v_cvt_f32_u32_e32 v6, s23
	s_mov_b32 s19, 0xc2fc0000
	s_lshl_b32 s1, s22, 9
	s_lshl_b32 s0, s23, 7
	v_sub_f32_e32 v6, 0xc0a00000, v6
	v_cmp_gt_f32_e32 vcc, s19, v6
	s_add_i32 s4, s0, s1
	s_and_b64 s[6:7], vcc, exec
	v_cndmask_b32_e32 v7, 0, v1, vcc
	v_add_f32_e32 v6, v6, v7
	v_exp_f32_e32 v6, v6
	s_cselect_b32 s1, 0xffffffc0, 0
	v_ashrrev_i32_e32 v30, 2, v132
	s_lshl_b32 s5, s21, 6
	v_ldexp_f32 v22, v6, s1
	v_sub_f32_e32 v8, 1.0, v22
	v_add_f32_e32 v6, -1.0, v8
	v_sub_f32_e32 v7, v6, v8
	v_add_f32_e32 v7, 1.0, v7
	v_sub_f32_e64 v6, -v22, v6
	v_add_f32_e32 v9, v6, v7
	v_frexp_mant_f32_e32 v6, v8
	s_mov_b32 s1, 0x3f2aaaab
	v_cmp_gt_f32_e32 vcc, s1, v6
	v_cvt_f64_f32_e32 v[6:7], v8
	v_frexp_exp_i32_f64_e32 v6, v[6:7]
	v_subbrev_co_u32_e32 v14, vcc, 0, v6, vcc
	v_sub_u32_e32 v6, 0, v14
	v_ldexp_f32 v7, v8, v6
	v_add_f32_e32 v8, -1.0, v7
	v_add_f32_e32 v10, 1.0, v7
	v_ldexp_f32 v6, v9, v6
	v_add_f32_e32 v9, 1.0, v8
	v_add_f32_e32 v11, -1.0, v10
	v_sub_f32_e32 v9, v7, v9
	v_sub_f32_e32 v7, v7, v11
	v_add_f32_e32 v9, v6, v9
	v_add_f32_e32 v6, v6, v7
	v_add_f32_e32 v15, v10, v6
	v_rcp_f32_e32 v17, v15
	v_sub_f32_e32 v7, v15, v10
	v_sub_f32_e32 v16, v6, v7
	v_add_f32_e32 v7, v8, v9
	v_mul_f32_e32 v19, v7, v17
	v_sub_f32_e32 v6, v7, v8
	v_mul_f32_e32 v8, v15, v19
	v_fma_f32 v10, v19, v15, -v8
	v_fmac_f32_e32 v10, v19, v16
	v_sub_f32_e32 v18, v9, v6
	v_add_f32_e32 v6, v8, v10
	v_sub_f32_e32 v9, v7, v6
	v_pk_add_f32 v[12:13], v[6:7], v[8:9] neg_lo:[0,1] neg_hi:[0,1]
	v_mov_b32_e32 v11, v6
	v_pk_add_f32 v[6:7], v[12:13], v[10:11] neg_lo:[0,1] neg_hi:[0,1]
	s_mov_b32 s1, 0x3f317218
	v_add_f32_e32 v7, v18, v7
	v_add_f32_e32 v6, v6, v7
	v_add_f32_e32 v7, v9, v6
	v_mul_f32_e32 v18, v17, v7
	v_mul_f32_e32 v8, v15, v18
	v_fma_f32 v10, v18, v15, -v8
	v_fmac_f32_e32 v10, v18, v16
	v_sub_f32_e32 v9, v9, v7
	v_add_f32_e32 v15, v6, v9
	v_add_f32_e32 v6, v8, v10
	v_sub_f32_e32 v9, v7, v6
	v_pk_add_f32 v[12:13], v[6:7], v[8:9] neg_lo:[0,1] neg_hi:[0,1]
	v_mov_b32_e32 v11, v6
	v_pk_add_f32 v[6:7], v[12:13], v[10:11] neg_lo:[0,1] neg_hi:[0,1]
	v_cmp_nlt_f32_e32 vcc, 1.0, v22
	v_add_f32_e32 v7, v15, v7
	v_add_f32_e32 v6, v6, v7
	v_add_f32_e32 v7, v19, v18
	v_add_f32_e32 v6, v9, v6
	v_sub_f32_e32 v8, v7, v19
	v_mul_f32_e32 v6, v17, v6
	v_sub_f32_e32 v8, v18, v8
	v_add_f32_e32 v8, v8, v6
	v_add_f32_e32 v10, v7, v8
	v_mul_f32_e32 v11, v10, v10
	v_fmamk_f32 v6, v11, 0x3e9b6dac, v235
	v_fmaak_f32 v155, v11, v6, 0x3f2aaada
	v_cvt_f32_i32_e32 v6, v14
	v_sub_f32_e32 v7, v10, v7
	v_sub_f32_e32 v7, v8, v7
	v_ldexp_f32 v12, v7, 1
	v_mul_f32_e32 v7, v10, v11
	v_ldexp_f32 v9, v10, 1
	v_pk_mul_f32 v[10:11], v[6:7], v[154:155]
	v_ashrrev_i32_e32 v31, 31, v30
	v_fma_f32 v8, v6, s1, -v10
	v_fmac_f32_e32 v8, 0xb102e308, v6
	v_pk_add_f32 v[6:7], v[10:11], v[8:9]
	s_mov_b32 s1, 0x33800000
	v_sub_f32_e32 v9, v7, v9
	v_sub_f32_e32 v9, v11, v9
	v_add_f32_e32 v13, v12, v9
	v_mov_b32_e32 v12, v10
	v_pk_add_f32 v[10:11], v[6:7], v[10:11] neg_lo:[0,1] neg_hi:[0,1]
	v_pk_add_f32 v[14:15], v[6:7], v[12:13]
	v_mov_b32_e32 v9, v6
	v_mov_b32_e32 v11, v15
	v_pk_add_f32 v[16:17], v[8:9], v[10:11] neg_lo:[0,1] neg_hi:[0,1]
	v_pk_add_f32 v[8:9], v[8:9], v[10:11]
	v_mov_b32_e32 v20, v7
	v_pk_add_f32 v[10:11], v[8:9], v[6:7] op_sel:[1,0] op_sel_hi:[0,1] neg_lo:[0,1] neg_hi:[0,1]
	v_pk_add_f32 v[18:19], v[14:15], v[10:11] op_sel_hi:[1,0] neg_lo:[0,1] neg_hi:[0,1]
	v_mov_b32_e32 v14, v15
	v_mov_b32_e32 v15, v9
	v_mov_b32_e32 v21, v10
	v_pk_add_f32 v[10:11], v[14:15], v[20:21] neg_lo:[0,1] neg_hi:[0,1]
	v_mov_b32_e32 v12, v13
	v_mov_b32_e32 v13, v6
	v_pk_add_f32 v[6:7], v[12:13], v[10:11] neg_lo:[0,1] neg_hi:[0,1]
	v_mov_b32_e32 v18, v16
	v_pk_add_f32 v[10:11], v[18:19], v[6:7]
	v_mov_b32_e32 v17, v9
	v_pk_add_f32 v[12:13], v[10:11], v[10:11] op_sel:[0,1] op_sel_hi:[1,0]
	v_mov_b32_e32 v37, s36
	v_pk_add_f32 v[8:9], v[8:9], v[12:13] op_sel:[1,0] op_sel_hi:[0,1]
	v_mov_b32_e32 v11, v8
	v_pk_add_f32 v[14:15], v[10:11], v[16:17] neg_lo:[0,1] neg_hi:[0,1]
	v_mov_b32_e32 v7, v12
	v_sub_f32_e32 v9, v10, v14
	v_pk_add_f32 v[6:7], v[6:7], v[14:15] neg_lo:[0,1] neg_hi:[0,1]
	v_sub_f32_e32 v9, v16, v9
	v_add_f32_e32 v6, v6, v9
	v_add_f32_e32 v6, v6, v7
	v_add_f32_e32 v6, v8, v6
	v_mov_b32_e32 v7, 0x7fc00000
	v_cndmask_b32_e32 v6, v7, v6, vcc
	v_cmp_neq_f32_e32 vcc, 1.0, v22
	v_mov_b32_e32 v7, 0xff800000
	v_mov_b64_e32 v[8:9], s[76:77]
	v_cndmask_b32_e32 v6, v7, v6, vcc
	v_cmp_gt_f32_e32 vcc, s1, v22
	s_lshl_b32 s1, s22, 13
	s_or_b32 s16, s5, s1
	v_cndmask_b32_e64 v36, v6, -v22, vcc
	v_lshl_add_u64 v[6:7], v[30:31], 0, s[16:17]
	v_mad_u64_u32 v[8:9], s[6:7], v6, s71, v[8:9]
	v_add_u32_e32 v38, 0x2400, v37
	v_and_b32_e32 v50, 3, v132
	v_add_u32_e32 v33, 0x2400, v38
	v_mad_i32_i24 v9, v7, s71, v9
	s_mov_b32 s1, s17
	v_lshl_add_u64 v[22:23], v[8:9], 0, s[0:1]
	v_add_u32_e32 v34, 0x2400, v33
	v_lshlrev_b32_e32 v156, 4, v50
	s_waitcnt vmcnt(4)
	v_lshlrev_b32_e32 v24, 5, v50
	v_mov_b32_e32 v25, v157
	v_lshl_add_u64 v[10:11], v[22:23], 0, v[156:157]
	v_add_u32_e32 v35, 0x2400, v34
	v_lshl_add_u64 v[26:27], v[22:23], 0, v[24:25]
	global_load_dwordx4 v[14:17], v[10:11], off
	global_load_dwordx4 v[18:21], v[10:11], off offset:64
	global_load_dwordx4 v[6:9], v[10:11], off offset:512
	s_nop 0
	global_load_dwordx4 v[10:13], v[10:11], off offset:576
	s_nop 0
	global_load_dwordx4 v[22:25], v[26:27], off offset:1040
	s_nop 0
	global_load_dwordx4 v[26:29], v[26:27], off offset:1024
	v_lshlrev_b32_e32 v39, 3, v50
	v_lshlrev_b32_e32 v63, 1, v30
	s_or_b32 s0, s4, s21
	s_ashr_i32 s1, s0, 31
	s_lshl_b64 s[0:1], s[0:1], 13
	s_add_u32 s4, s89, s0
	v_and_b32_e32 v32, 15, v130
	s_waitcnt vmcnt(5)
	v_lshlrev_b32_e32 v46, 16, v14
	s_waitcnt vmcnt(4)
; __device__ __forceinline__ bf16_t f2bf(float f) { return (bf16_t)(pk2(f, 0.f) & 0xffffu); }
; __device__ __forceinline__ void ret_unit(const Ctx& X, LAS unsigned char* hl, int b, int c, int h, int tid_h, int w4, int lane) {
;     ...
;         float qr1[8], qr2[8], kr1[8], kr2[8], qe1[8], qe2[8];
; #pragma unroll
;         for (int e = 0; e < 8; ++e) {
;             const float inv = exp2f(-(float)(d0 + e) * (13.287712379549449f / 32.0f));
;             const float rev = __builtin_amdgcn_fractf(pos * inv * 0.15915494309189535f); const float sn = __builtin_amdgcn_sinf(rev), cs = __builtin_amdgcn_cosf(rev);
;             qr1[e] = qa[e] * cs - qb[e] * sn; qr2[e] = qa[e] * sn + qb[e] * cs;
;             kr1[e] = (ka[e] * cs - kb[e] * sn) * 0.125f; kr2[e] = (ka[e] * sn + kb[e] * cs) * 0.125f;
;             qe1[e] = qr1[e] * qd; qe2[e] = qr2[e] * qd;
;             KDT[(d0 + e) * LT + i] = f2bf(kr1[e] * kd); KDT[(d0 + 32 + e) * LT + i] = f2bf(kr2[e] * kd);
;             VT[(sg * 16 + e) * LT + i] = f2bf(va[e]); VT[(sg * 16 + 8 + e) * LT + i] = f2bf(vb[e]);
;         }
	v_lshlrev_b32_e32 v47, 16, v18
	s_waitcnt vmcnt(1)
	v_lshlrev_b32_e32 v59, 16, v23
	v_and_b32_e32 v60, 0xffff0000, v23
	v_add_u32_e32 v23, s5, v30
	s_waitcnt vmcnt(0)
	v_lshlrev_b32_e32 v55, 16, v28
	v_and_b32_e32 v56, 0xffff0000, v28
	v_cvt_f32_i32_e32 v28, v23
	v_add_u32_e32 v23, 1, v30
	v_cvt_f32_i32_e32 v23, v23
	v_lshlrev_b32_e32 v57, 16, v22
	v_and_b32_e32 v58, 0xffff0000, v22
	v_lshlrev_b32_e32 v42, 16, v25
	v_mul_f32_e32 v23, v36, v23
	v_mul_f32_e32 v23, 0x3fb8aa3b, v23
	v_and_b32_e32 v22, 0xffff0000, v25
	v_exp_f32_e32 v25, v23
	v_sub_u32_e32 v23, 63, v30
	v_cvt_f32_i32_e32 v23, v23
	v_lshlrev_b32_e32 v53, 16, v27
	v_and_b32_e32 v54, 0xffff0000, v27
	v_lshlrev_b32_e32 v61, 16, v24
	v_mul_f32_e32 v23, v36, v23
	v_mul_f32_e32 v23, 0x3fb8aa3b, v23
	v_exp_f32_e32 v27, v23
	v_cvt_f32_ubyte0_e32 v23, v39
	v_and_b32_e32 v62, 0xffff0000, v24
	v_mul_f32_e32 v24, 0xbed49a78, v23
	v_cmp_gt_f32_e32 vcc, s19, v24
	v_lshlrev_b32_e32 v51, 16, v26
	v_and_b32_e32 v52, 0xffff0000, v26
	v_cndmask_b32_e32 v24, 0, v1, vcc
	v_fmac_f32_e32 v24, 0xbed49a78, v23
	v_exp_f32_e32 v23, v24
	v_cndmask_b32_e32 v24, 0, v233, vcc
	v_lshlrev_b32_e32 v41, 16, v29
	v_and_b32_e32 v26, 0xffff0000, v29
	v_ldexp_f32 v23, v23, v24
	v_mul_f32_e32 v23, v23, v28
	v_mul_f32_e32 v23, 0.15915494, v23
	v_fract_f32_e32 v23, v23
	v_sin_f32_e32 v45, v23
	v_cos_f32_e32 v44, v23
	s_addc_u32 s5, s78, s1
	v_pk_mul_f32 v[48:49], v[44:45], v[46:47]
	s_nop 0
	v_sub_f32_e32 v43, v48, v49
	v_mov_b32_e32 v48, v45
	v_mov_b32_e32 v49, v44
	v_pk_mul_f32 v[46:47], v[48:49], v[46:47]
	v_mul_f32_e32 v24, v25, v43
	v_add_f32_e32 v40, v46, v47
	v_lshlrev_b32_e32 v47, 16, v10
	v_lshlrev_b32_e32 v46, 16, v6
	v_pk_mul_f32 v[44:45], v[44:45], v[46:47]
	s_nop 0
	v_sub_f32_e32 v23, v44, v45
	v_mul_f32_e32 v31, 0x3e000000, v23
	v_pk_mul_f32 v[44:45], v[48:49], v[46:47]
	v_and_b32_e32 v49, 0xffff0000, v18
	v_add_f32_e32 v23, v44, v45
	v_mul_f32_e32 v44, v27, v31
	v_mul_u32_u24_e32 v45, 0x480, v50
	v_mul_f32_e32 v29, 0x3e000000, v23
	v_cvt_pk_bf16_f32 v44, v44, v157
	v_add3_u32 v45, v33, v45, v63
	ds_write_b16 v45, v44
	v_mul_f32_e32 v44, v27, v29
	v_cvt_pk_bf16_f32 v44, v44, v157
	ds_write_b16 v45, v44 offset:4608
	v_mul_u32_u24_e32 v44, 0x900, v50
	v_cvt_pk_bf16_f32 v45, v51, v157
	v_add3_u32 v44, v34, v44, v63
	ds_write_b16 v44, v45
	v_cvt_pk_bf16_f32 v45, v57, v157
	ds_write_b16 v44, v45 offset:1152
	v_or_b32_e32 v45, 1, v39
	v_cvt_f32_ubyte0_e32 v46, v45
	v_mul_f32_e32 v47, 0xbed49a78, v46
	v_cmp_gt_f32_e32 vcc, s19, v47
	v_and_b32_e32 v48, 0xffff0000, v14
	v_mul_u32_u24_e32 v18, 0x90, v45
	v_cndmask_b32_e32 v47, 0, v1, vcc
	v_fmac_f32_e32 v47, 0xbed49a78, v46
	v_exp_f32_e32 v46, v47
	v_cndmask_b32_e32 v47, 0, v233, vcc
	v_add3_u32 v45, v33, v18, v63
	v_mul_f32_e32 v23, v25, v40
	v_ldexp_f32 v46, v46, v47
	v_mul_f32_e32 v46, v46, v28
	v_mul_f32_e32 v46, 0.15915494, v46
	v_fract_f32_e32 v46, v46
	v_sin_f32_e32 v47, v46
	v_cos_f32_e32 v46, v46
	s_nop 0
	v_pk_mul_f32 v[50:51], v[46:47], v[48:49]
	s_nop 0
	v_sub_f32_e32 v57, v50, v51
	v_mov_b32_e32 v50, v47
	v_mov_b32_e32 v51, v46
	v_pk_mul_f32 v[48:49], v[50:51], v[48:49]
	s_nop 0
	v_add_f32_e32 v64, v48, v49
	v_and_b32_e32 v49, 0xffff0000, v10
	v_and_b32_e32 v48, 0xffff0000, v6
	v_pk_mul_f32 v[46:47], v[46:47], v[48:49]
	v_mul_f32_e32 v10, v25, v57
	v_sub_f32_e32 v6, v46, v47
	v_mul_f32_e32 v65, 0x3e000000, v6
	v_pk_mul_f32 v[46:47], v[50:51], v[48:49]
	v_mul_f32_e32 v14, v27, v65
	v_add_f32_e32 v6, v46, v47
	v_mul_f32_e32 v66, 0x3e000000, v6
	v_cvt_pk_bf16_f32 v14, v14, v157
	ds_write_b16 v45, v14
	v_mul_f32_e32 v14, v27, v66
	v_cvt_pk_bf16_f32 v14, v14, v157
	ds_write_b16 v45, v14 offset:4608
	v_cvt_pk_bf16_f32 v14, v52, v157
	ds_write_b16 v44, v14 offset:144
	v_cvt_pk_bf16_f32 v14, v58, v157
	ds_write_b16 v44, v14 offset:1296
	v_or_b32_e32 v14, 2, v39
	v_cvt_f32_ubyte0_e32 v14, v14
	v_mul_f32_e32 v18, 0xbed49a78, v14
	v_cmp_gt_f32_e32 vcc, s19, v18
	v_lshlrev_b32_e32 v49, 16, v19
	v_lshlrev_b32_e32 v48, 16, v15
	v_cndmask_b32_e32 v18, 0, v1, vcc
	v_fmac_f32_e32 v18, 0xbed49a78, v14
	v_exp_f32_e32 v14, v18
	v_cndmask_b32_e32 v18, 0, v233, vcc
	v_and_b32_e32 v19, 0xffff0000, v19
	v_mul_f32_e32 v6, v25, v64
	v_ldexp_f32 v14, v14, v18
	v_mul_f32_e32 v14, v14, v28
	v_mul_f32_e32 v14, 0.15915494, v14
	v_fract_f32_e32 v14, v14
	v_sin_f32_e32 v47, v14
	v_cos_f32_e32 v46, v14
	s_nop 0
	v_pk_mul_f32 v[50:51], v[46:47], v[48:49]
	s_nop 0
	v_sub_f32_e32 v52, v50, v51
	v_mov_b32_e32 v50, v47
	v_mov_b32_e32 v51, v46
	v_pk_mul_f32 v[48:49], v[50:51], v[48:49]
	s_nop 0
	v_add_f32_e32 v58, v48, v49
	v_lshlrev_b32_e32 v49, 16, v11
	v_lshlrev_b32_e32 v48, 16, v7
	v_pk_mul_f32 v[46:47], v[46:47], v[48:49]
	s_nop 0
	v_sub_f32_e32 v14, v46, v47
	v_pk_mul_f32 v[46:47], v[50:51], v[48:49]
	v_mul_f32_e32 v63, 0x3e000000, v14
	v_add_f32_e32 v14, v46, v47
	v_mul_f32_e32 v48, 0x3e000000, v14
	v_mul_f32_e32 v14, v27, v63
	v_cvt_pk_bf16_f32 v14, v14, v157
	ds_write_b16 v45, v14 offset:144
	v_mul_f32_e32 v14, v27, v48
	v_cvt_pk_bf16_f32 v14, v14, v157
	ds_write_b16 v45, v14 offset:4752
	v_cvt_pk_bf16_f32 v14, v53, v157
	ds_write_b16 v44, v14 offset:288
	v_cvt_pk_bf16_f32 v14, v59, v157
	ds_write_b16 v44, v14 offset:1440
	v_or_b32_e32 v14, 3, v39
	v_cvt_f32_ubyte0_e32 v14, v14
	v_mul_f32_e32 v18, 0xbed49a78, v14
	v_cmp_gt_f32_e32 vcc, s19, v18
	v_mul_f32_e32 v49, v25, v52
	v_mul_f32_e32 v50, v25, v58
	v_cndmask_b32_e32 v18, 0, v1, vcc
	v_fmac_f32_e32 v18, 0xbed49a78, v14
	v_exp_f32_e32 v14, v18
	v_cndmask_b32_e32 v18, 0, v233, vcc
	v_ldexp_f32 v14, v14, v18
	v_mul_f32_e32 v14, v14, v28
	v_mul_f32_e32 v14, 0.15915494, v14
	v_fract_f32_e32 v14, v14
	v_sin_f32_e32 v47, v14
; __device__ __forceinline__ bf16_t f2bf(float f) { return (bf16_t)(pk2(f, 0.f) & 0xffffu); }
; __device__ __forceinline__ void ret_unit(const Ctx& X, LAS unsigned char* hl, int b, int c, int h, int tid_h, int w4, int lane) {
;     ...
;         for (int e = 0; e < 8; ++e) {
;             const float inv = exp2f(-(float)(d0 + e) * (13.287712379549449f / 32.0f));
;             const float rev = __builtin_amdgcn_fractf(pos * inv * 0.15915494309189535f); const float sn = __builtin_amdgcn_sinf(rev), cs = __builtin_amdgcn_cosf(rev);
;             qr1[e] = qa[e] * cs - qb[e] * sn; qr2[e] = qa[e] * sn + qb[e] * cs;
;             kr1[e] = (ka[e] * cs - kb[e] * sn) * 0.125f; kr2[e] = (ka[e] * sn + kb[e] * cs) * 0.125f;
;             qe1[e] = qr1[e] * qd; qe2[e] = qr2[e] * qd;
;             KDT[(d0 + e) * LT + i] = f2bf(kr1[e] * kd); KDT[(d0 + 32 + e) * LT + i] = f2bf(kr2[e] * kd);
;             VT[(sg * 16 + e) * LT + i] = f2bf(va[e]); VT[(sg * 16 + 8 + e) * LT + i] = f2bf(vb[e]);
;         }
	v_cos_f32_e32 v46, v14
	v_and_b32_e32 v18, 0xffff0000, v15
	v_pk_mul_f32 v[14:15], v[46:47], v[18:19]
	s_nop 0
	v_sub_f32_e32 v51, v14, v15
	v_mov_b32_e32 v14, v47
	v_mov_b32_e32 v15, v46
	v_pk_mul_f32 v[18:19], v[14:15], v[18:19]
	v_mul_f32_e32 v59, v25, v51
	v_add_f32_e32 v53, v18, v19
	v_and_b32_e32 v19, 0xffff0000, v11
	v_and_b32_e32 v18, 0xffff0000, v7
	v_pk_mul_f32 v[46:47], v[46:47], v[18:19]
	v_pk_mul_f32 v[14:15], v[14:15], v[18:19]
	v_sub_f32_e32 v7, v46, v47
	v_mul_f32_e32 v7, 0x3e000000, v7
	v_add_f32_e32 v11, v14, v15
	v_mul_f32_e32 v14, v27, v7
	v_mul_f32_e32 v11, 0x3e000000, v11
	v_cvt_pk_bf16_f32 v14, v14, v157
	ds_write_b16 v45, v14 offset:288
	v_mul_f32_e32 v14, v27, v11
	v_cvt_pk_bf16_f32 v14, v14, v157
	ds_write_b16 v45, v14 offset:4896
	v_cvt_pk_bf16_f32 v14, v54, v157
	ds_write_b16 v44, v14 offset:432
	v_cvt_pk_bf16_f32 v14, v60, v157
	ds_write_b16 v44, v14 offset:1584
	v_or_b32_e32 v14, 4, v39
	v_cvt_f32_ubyte0_e32 v14, v14
	v_mul_f32_e32 v15, 0xbed49a78, v14
	v_cmp_gt_f32_e32 vcc, s19, v15
	v_lshlrev_b32_e32 v19, 16, v20
	v_lshlrev_b32_e32 v18, 16, v16
	v_cndmask_b32_e32 v15, 0, v1, vcc
	v_fmac_f32_e32 v15, 0xbed49a78, v14
	v_exp_f32_e32 v14, v15
	v_cndmask_b32_e32 v15, 0, v233, vcc
	v_mul_f32_e32 v67, v25, v53
	v_ldexp_f32 v14, v14, v15
	v_mul_f32_e32 v14, v14, v28
	v_mul_f32_e32 v14, 0.15915494, v14
	v_fract_f32_e32 v14, v14
	v_sin_f32_e32 v15, v14
	v_cos_f32_e32 v14, v14
	s_nop 0
	v_pk_mul_f32 v[46:47], v[14:15], v[18:19]
	s_nop 0
	v_sub_f32_e32 v54, v46, v47
	v_mov_b32_e32 v46, v15
	v_mov_b32_e32 v47, v14
	v_pk_mul_f32 v[18:19], v[46:47], v[18:19]
	v_mul_f32_e32 v70, v25, v54
	v_add_f32_e32 v60, v18, v19
	v_lshlrev_b32_e32 v19, 16, v12
	v_lshlrev_b32_e32 v18, 16, v8
	v_pk_mul_f32 v[14:15], v[14:15], v[18:19]
	v_mul_f32_e32 v71, v25, v60
	v_sub_f32_e32 v14, v14, v15
	v_mul_f32_e32 v68, 0x3e000000, v14
	v_pk_mul_f32 v[14:15], v[46:47], v[18:19]
	v_and_b32_e32 v19, 0xffff0000, v20
	v_add_f32_e32 v14, v14, v15
	v_mul_f32_e32 v69, 0x3e000000, v14
	v_mul_f32_e32 v14, v27, v68
	v_cvt_pk_bf16_f32 v14, v14, v157
	ds_write_b16 v45, v14 offset:432
	v_mul_f32_e32 v14, v27, v69
	v_cvt_pk_bf16_f32 v14, v14, v157
	ds_write_b16 v45, v14 offset:5040
	v_cvt_pk_bf16_f32 v14, v55, v157
	ds_write_b16 v44, v14 offset:576
	v_cvt_pk_bf16_f32 v14, v61, v157
	ds_write_b16 v44, v14 offset:1728
	v_or_b32_e32 v14, 5, v39
	v_cvt_f32_ubyte0_e32 v14, v14
	v_mul_f32_e32 v15, 0xbed49a78, v14
	v_cmp_gt_f32_e32 vcc, s19, v15
	v_and_b32_e32 v18, 0xffff0000, v16
	s_nop 0
	v_cndmask_b32_e32 v15, 0, v1, vcc
	v_fmac_f32_e32 v15, 0xbed49a78, v14
	v_exp_f32_e32 v14, v15
	v_cndmask_b32_e32 v15, 0, v233, vcc
	v_ldexp_f32 v14, v14, v15
	v_mul_f32_e32 v14, v14, v28
	v_mul_f32_e32 v14, 0.15915494, v14
	v_fract_f32_e32 v14, v14
	v_sin_f32_e32 v15, v14
	v_cos_f32_e32 v14, v14
	s_nop 0
	v_pk_mul_f32 v[46:47], v[14:15], v[18:19]
	s_nop 0
	v_sub_f32_e32 v20, v46, v47
	v_mov_b32_e32 v46, v15
	v_mov_b32_e32 v47, v14
	v_pk_mul_f32 v[18:19], v[46:47], v[18:19]
	v_mul_f32_e32 v73, v25, v20
	v_add_f32_e32 v55, v18, v19
	v_and_b32_e32 v19, 0xffff0000, v12
	v_and_b32_e32 v18, 0xffff0000, v8
	v_pk_mul_f32 v[14:15], v[14:15], v[18:19]
	v_mul_f32_e32 v74, v25, v55
	v_sub_f32_e32 v8, v14, v15
	v_pk_mul_f32 v[14:15], v[46:47], v[18:19]
	v_mul_f32_e32 v61, 0x3e000000, v8
	v_add_f32_e32 v8, v14, v15
	v_mul_f32_e32 v72, 0x3e000000, v8
	v_mul_f32_e32 v8, v27, v61
	v_cvt_pk_bf16_f32 v8, v8, v157
	ds_write_b16 v45, v8 offset:576
	v_mul_f32_e32 v8, v27, v72
	v_cvt_pk_bf16_f32 v8, v8, v157
	ds_write_b16 v45, v8 offset:5184
	v_cvt_pk_bf16_f32 v8, v56, v157
	ds_write_b16 v44, v8 offset:720
	v_cvt_pk_bf16_f32 v8, v62, v157
	ds_write_b16 v44, v8 offset:1872
	v_or_b32_e32 v8, 6, v39
	v_cvt_f32_ubyte0_e32 v8, v8
	v_mul_f32_e32 v12, 0xbed49a78, v8
	v_cmp_gt_f32_e32 vcc, s19, v12
	v_lshlrev_b32_e32 v19, 16, v21
	v_lshlrev_b32_e32 v18, 16, v17
	v_cndmask_b32_e32 v12, 0, v1, vcc
	v_fmac_f32_e32 v12, 0xbed49a78, v8
	v_exp_f32_e32 v8, v12
	v_cndmask_b32_e32 v12, 0, v233, vcc
	v_ldexp_f32 v8, v8, v12
	v_mul_f32_e32 v8, v8, v28
	v_mul_f32_e32 v8, 0.15915494, v8
	v_fract_f32_e32 v8, v8
	v_sin_f32_e32 v15, v8
	v_cos_f32_e32 v14, v8
	s_nop 0
	v_pk_mul_f32 v[46:47], v[14:15], v[18:19]
	s_nop 0
	v_sub_f32_e32 v56, v46, v47
	v_mov_b32_e32 v46, v15
	v_mov_b32_e32 v47, v14
	v_pk_mul_f32 v[18:19], v[46:47], v[18:19]
	s_nop 0
; #define LAS __attribute__((address_space(3)))
; __device__ __forceinline__ bf16_t f2bf(float f) { return (bf16_t)(pk2(f, 0.f) & 0xffffu); }
; __device__ __forceinline__ u32x4 pack8(const float (&f)[8]) { u32x4 w; w.x = pk2(f[0], f[1]); w.y = pk2(f[2], f[3]); w.z = pk2(f[4], f[5]); w.w = pk2(f[6], f[7]); return w; }
; #define LBAR() do { asm volatile("s_waitcnt lgkmcnt(0)" ::: "memory"); __builtin_amdgcn_s_barrier(); asm volatile("" ::: "memory"); } while (0)
; __device__ __forceinline__ void ret_unit(const Ctx& X, LAS unsigned char* hl, int b, int c, int h, int tid_h, int w4, int lane) {
;     ...
;         for (int e = 0; e < 8; ++e) {
;             const float inv = exp2f(-(float)(d0 + e) * (13.287712379549449f / 32.0f));
;             const float rev = __builtin_amdgcn_fractf(pos * inv * 0.15915494309189535f); const float sn = __builtin_amdgcn_sinf(rev), cs = __builtin_amdgcn_cosf(rev);
;             qr1[e] = qa[e] * cs - qb[e] * sn; qr2[e] = qa[e] * sn + qb[e] * cs;
;             kr1[e] = (ka[e] * cs - kb[e] * sn) * 0.125f; kr2[e] = (ka[e] * sn + kb[e] * cs) * 0.125f;
;             qe1[e] = qr1[e] * qd; qe2[e] = qr2[e] * qd;
;             KDT[(d0 + e) * LT + i] = f2bf(kr1[e] * kd); KDT[(d0 + 32 + e) * LT + i] = f2bf(kr2[e] * kd);
;             VT[(sg * 16 + e) * LT + i] = f2bf(va[e]); VT[(sg * 16 + 8 + e) * LT + i] = f2bf(vb[e]);
;         }
;         *(LAS u32x4*)(QR + i * LT + d0) = pack8(qr1); *(LAS u32x4*)(QR + i * LT + d0 + 32) = pack8(qr2);
;         *(LAS u32x4*)(KR + i * LT + d0) = pack8(kr1); *(LAS u32x4*)(KR + i * LT + d0 + 32) = pack8(kr2);
;         bf16_t* qe = WSP(bf16_t, WS_QEFF) + (size_t)uid * 4096 + i * 64;
;         *(u32x4*)(qe + d0) = pack8(qe1); *(u32x4*)(qe + d0 + 32) = pack8(qe2);
;     }
;     LBAR();
; __device__ __forceinline__ void mixer_local_phase(const Ctx& X, LAS unsigned char* lds, int layer, int tid, int wave, int lane) {
;     ...
;     for (int it_ = 0; it_ < nit_; ++it_) {
;         const int u = (int)blockIdx.x + (int)gridDim.x * ((it_ + (int)(blockIdx.x >> 3)) % nit_);
;         if (u >= 3584) continue;
;         asm volatile("" : "+v"(tid_h), "+v"(lane), "+v"(tid));
;         if (u < 3072) { const int mixer = u >> 10, idx = u & 1023, hp = idx & 1, cb = idx >> 1, b = cb >> 7, c = cb & 127, h = hp * 2 + hs;
	v_add_f32_e32 v62, v18, v19
	v_lshlrev_b32_e32 v19, 16, v13
	v_lshlrev_b32_e32 v18, 16, v9
	v_pk_mul_f32 v[14:15], v[14:15], v[18:19]
	v_and_b32_e32 v13, 0xffff0000, v13
	v_sub_f32_e32 v8, v14, v15
	v_pk_mul_f32 v[14:15], v[46:47], v[18:19]
	v_mul_f32_e32 v75, 0x3e000000, v8
	v_add_f32_e32 v8, v14, v15
	v_mul_f32_e32 v46, 0x3e000000, v8
	v_mul_f32_e32 v8, v27, v75
	v_cvt_pk_bf16_f32 v8, v8, v157
	ds_write_b16 v45, v8 offset:720
	v_mul_f32_e32 v8, v27, v46
	v_cvt_pk_bf16_f32 v8, v8, v157
	ds_write_b16 v45, v8 offset:5328
	v_cvt_pk_bf16_f32 v8, v41, v157
	ds_write_b16 v44, v8 offset:864
	v_cvt_pk_bf16_f32 v8, v42, v157
	ds_write_b16 v44, v8 offset:2016
	v_or_b32_e32 v8, 7, v39
	v_cvt_f32_ubyte0_e32 v8, v8
	v_mul_f32_e32 v12, 0xbed49a78, v8
	v_cmp_gt_f32_e32 vcc, s19, v12
	v_and_b32_e32 v19, 0xffff0000, v21
	v_and_b32_e32 v18, 0xffff0000, v17
	v_cndmask_b32_e32 v12, 0, v1, vcc
	v_fmac_f32_e32 v12, 0xbed49a78, v8
	v_exp_f32_e32 v8, v12
	v_cndmask_b32_e32 v12, 0, v233, vcc
	v_mul_f32_e32 v47, v25, v56
	v_mul_f32_e32 v76, v25, v62
	v_ldexp_f32 v8, v8, v12
	v_mul_f32_e32 v8, v8, v28
	v_mul_f32_e32 v8, 0.15915494, v8
	v_fract_f32_e32 v8, v8
	v_sin_f32_e32 v15, v8
	v_cos_f32_e32 v14, v8
	v_and_b32_e32 v12, 0xffff0000, v9
	v_readlane_b32 s19, v255, 26
	v_pk_mul_f32 v[16:17], v[14:15], v[18:19]
	v_pk_mul_f32 v[8:9], v[14:15], v[12:13]
	v_sub_f32_e32 v21, v16, v17
	v_mov_b32_e32 v16, v15
	v_mov_b32_e32 v17, v14
	v_sub_f32_e32 v8, v8, v9
	v_mul_f32_e32 v28, 0x3e000000, v8
	v_pk_mul_f32 v[8:9], v[16:17], v[12:13]
	v_pk_mul_f32 v[18:19], v[16:17], v[18:19]
	v_add_f32_e32 v8, v8, v9
	v_mul_f32_e32 v9, v27, v28
	v_mul_f32_e32 v8, 0x3e000000, v8
	v_cvt_pk_bf16_f32 v9, v9, v157
	ds_write_b16 v45, v9 offset:864
	v_mul_f32_e32 v9, v27, v8
	v_cvt_pk_bf16_f32 v9, v9, v157
	ds_write_b16 v45, v9 offset:5472
	v_cvt_pk_bf16_f32 v9, v26, v157
	ds_write_b16 v44, v9 offset:1008
	v_cvt_pk_bf16_f32 v9, v22, v157
	ds_write_b16 v44, v9 offset:2160
	v_mul_lo_u32 v9, v30, s44
	v_cvt_pk_bf16_f32 v12, v43, v57
	v_cvt_pk_bf16_f32 v13, v52, v51
	v_cvt_pk_bf16_f32 v14, v54, v20
	v_cvt_pk_bf16_f32 v15, v56, v21
	v_add3_u32 v20, v37, v9, v156
	v_add_f32_e32 v19, v18, v19
	ds_write_b128 v20, v[12:15]
	v_cvt_pk_bf16_f32 v12, v40, v64
	v_cvt_pk_bf16_f32 v13, v58, v53
	v_cvt_pk_bf16_f32 v14, v60, v55
	v_cvt_pk_bf16_f32 v15, v62, v19
	ds_write_b128 v20, v[12:15] offset:64
	v_cvt_pk_bf16_f32 v12, v31, v65
	v_cvt_pk_bf16_f32 v13, v63, v7
	v_cvt_pk_bf16_f32 v14, v68, v61
	v_cvt_pk_bf16_f32 v15, v75, v28
	v_add3_u32 v7, v38, v9, v156
	ds_write_b128 v7, v[12:15]
	v_cvt_pk_bf16_f32 v12, v29, v66
	v_cvt_pk_bf16_f32 v13, v48, v11
	v_cvt_pk_bf16_f32 v14, v69, v72
	v_cvt_pk_bf16_f32 v15, v46, v8
	v_lshlrev_b32_e32 v8, 6, v30
	v_ashrrev_i32_e32 v9, 31, v8
	ds_write_b128 v7, v[12:15] offset:64
	v_lshl_add_u64 v[12:13], v[8:9], 1, s[4:5]
	v_lshl_add_u64 v[12:13], v[12:13], 0, v[156:157]
	v_mul_f32_e32 v16, v25, v21
	v_cvt_pk_bf16_f32 v8, v24, v10
	v_cvt_pk_bf16_f32 v9, v49, v59
	v_cvt_pk_bf16_f32 v10, v70, v73
	v_cvt_pk_bf16_f32 v11, v47, v16
	global_store_dwordx4 v[12:13], v[8:11], off
	v_cvt_pk_bf16_f32 v6, v23, v6
	v_mul_f32_e32 v17, v25, v19
	v_cvt_pk_bf16_f32 v7, v50, v67
	v_and_b32_e32 v20, -16, v130
	v_cvt_pk_bf16_f32 v8, v71, v74
	v_cvt_pk_bf16_f32 v9, v76, v17
	global_store_dwordx4 v[12:13], v[6:9], off offset:64
	v_add_u32_e32 v29, v38, v20
	s_waitcnt lgkmcnt(0)
	s_barrier
	s_add_i32 s98, s20, 1
	s_cmp_ge_u32 s98, s70
	s_cbranch_scc1 .LpfR_done
	s_add_i32 s98, s98, s37
	s_mul_hi_u32 s99, s98, s87
	s_mul_i32 s99, s99, s70
	s_sub_i32 s98, s98, s99
	s_sub_i32 s99, s98, s70
	s_cmp_ge_u32 s98, s70
	s_cselect_b32 s98, s99, s98
	s_sub_i32 s99, s98, s70
	s_cmp_ge_u32 s98, s70
	s_cselect_b32 s98, s99, s98
	s_mul_i32 s98, s98, s18
	s_add_i32 s98, s98, s2
	v_lshrrev_b32_e32 v237, 3, v224
	v_and_b32_e32 v238, 7, v224
	s_cmpk_ge_u32 s98, 0xc00
	s_cbranch_scc1 .LpfR_conf
	s_lshr_b32 s99, s98, 10
	s_and_b32 s98, s98, 0x3ff
	s_and_b32 s100, s98, 1
	s_lshr_b32 s98, s98, 1
	s_cmp_eq_u32 s99, 2
	s_mul_i32 s99, s99, 0xc00
	s_cselect_b32 s101, 0x400, 0
	s_sub_u32 s99, s99, s101
	s_lshl_b32 s100, s100, 8
	s_add_u32 s99, s99, s100
	v_min_u32_e32 v238, 5, v238
	v_lshrrev_b32_e32 v239, 1, v238
	v_and_b32_e32 v238, 1, v238
	v_lshlrev_b32_e32 v239, 9, v239
	v_lshl_or_b32 v238, v238, 7, v239
	s_mov_b32 s101, 0
	s_branch .LpfR_go
